# P5 layer-1: the freshly written 'out' rows loaded normally as well (nt kept for the cold residual rows)
# baseline (speedup 1.0000x reference)
.LBB0_778:
	s_add_i32 s13, s40, s56
	s_cmpk_lt_i32 s13, 0x4000
	s_cselect_b32 s42, s13, s40
	s_ashr_i32 s41, s40, 31
	s_lshl_b64 s[38:39], s[40:41], 6
	s_add_u32 s44, s8, s38
	s_addc_u32 s45, s9, s39
	global_load_dwordx4 v[18:21], v1, s[44:45] offset:48
	global_load_dwordx4 v[22:25], v1, s[44:45] offset:32
	global_load_dwordx4 v[26:29], v1, s[44:45] offset:16
	global_load_dwordx4 v[30:33], v1, s[44:45]
	s_ashr_i32 s43, s42, 31
	s_lshl_b64 s[38:39], s[42:43], 6
	s_add_u32 s38, s8, s38
	s_addc_u32 s39, s9, s39
	s_lshl_b64 s[46:47], s[40:41], 11
	s_lshl_b64 s[50:51], s[42:43], 11
	v_lshl_add_u64 v[44:45], v[46:47], 0, s[46:47]
	v_lshl_add_u64 v[60:61], v[48:49], 0, s[46:47]
	v_lshl_add_u64 v[42:43], v[46:47], 0, s[50:51]
	v_lshl_add_u64 v[66:67], v[48:49], 0, s[50:51]
	s_lshl_b64 s[44:45], s[40:41], 12
	s_cmpk_gt_i32 s13, 0x3fff
	s_waitcnt vmcnt(0)
	v_add_f32_e32 v22, v22, v23
	v_add_f32_e32 v24, v24, v25
	v_mov_b32_e32 v34, v31
	v_mov_b32_e32 v35, v32
	v_mov_b32_e32 v31, v33
	v_mov_b32_e32 v32, v27
	v_mov_b32_e32 v33, v28
	v_mov_b32_e32 v27, v29
	v_pk_add_f32 v[30:31], v[34:35], v[30:31]
	v_pk_add_f32 v[26:27], v[32:33], v[26:27]
	v_pk_add_f32 v[30:31], v[30:31], v[30:31] op_sel:[0,1] op_sel_hi:[1,0]
	v_pk_add_f32 v[26:27], v[26:27], v[26:27] op_sel:[0,1] op_sel_hi:[1,0]
	v_mov_b32_e32 v31, v18
	v_mov_b32_e32 v27, v19
	v_mov_b32_e32 v23, v20
	v_mov_b32_e32 v25, v21
	v_pk_add_f32 v[18:19], v[30:31], v[26:27]
	v_pk_add_f32 v[20:21], v[22:23], v[24:25]
	s_nop 0
	v_pk_add_f32 v[18:19], v[18:19], v[20:21]
	s_nop 0
	v_add_f32_e32 v0, v18, v19
	v_fmamk_f32 v0, v0, 0x3a800000, v227
	v_cmp_gt_f32_e32 vcc, s7, v0
	v_mul_f32_e32 v18, 0x4f800000, v0
	s_nop 0
	v_cndmask_b32_e32 v0, v0, v18, vcc
	v_sqrt_f32_e32 v34, v0
	global_load_dwordx4 v[18:21], v1, s[38:39] offset:48
	global_load_dwordx4 v[22:25], v1, s[38:39] offset:32
	global_load_dwordx4 v[26:29], v1, s[38:39] offset:16
	global_load_dwordx4 v[30:33], v1, s[38:39]
	v_add_u32_e32 v36, -1, v34
	v_fma_f32 v37, -v36, v34, v0
	v_add_u32_e32 v35, 1, v34
	v_cmp_ge_f32_e64 s[38:39], 0, v37
	s_nop 1
	v_cndmask_b32_e64 v36, v34, v36, s[38:39]
	v_fma_f32 v34, -v35, v34, v0
	v_cmp_lt_f32_e64 s[38:39], 0, v34
	s_nop 1
	v_cndmask_b32_e64 v34, v36, v35, s[38:39]
	v_mul_f32_e32 v35, 0x37800000, v34
	v_cndmask_b32_e32 v34, v34, v35, vcc
	v_cmp_class_f32_e32 vcc, v0, v228
	s_nop 1
	v_cndmask_b32_e32 v0, v34, v0, vcc
	v_div_scale_f32 v34, s[38:39], v0, v0, 1.0
	v_rcp_f32_e32 v35, v34
	s_mov_b64 s[38:39], -1
	v_fma_f32 v36, -v34, v35, 1.0
	v_fmac_f32_e32 v35, v36, v35
	v_div_scale_f32 v36, vcc, 1.0, v0, 1.0
	v_mul_f32_e32 v37, v36, v35
	v_fma_f32 v38, -v34, v37, v36
	v_fmac_f32_e32 v37, v38, v35
	v_fma_f32 v34, -v34, v37, v36
	v_div_fmas_f32 v34, v34, v35, v37
	v_div_fixup_f32 v0, v34, v0, 1.0
	global_load_dwordx2 v[34:35], v[60:61], off nt
	global_load_dwordx2 v[52:53], v[66:67], off nt
	global_load_dwordx2 v[38:39], v[44:45], off
	global_load_dwordx2 v[54:55], v[42:43], off
	s_waitcnt vmcnt(3)
	v_lshlrev_b32_e32 v36, 16, v34
	s_waitcnt vmcnt(1)
	v_lshlrev_b32_e32 v40, 16, v38
	v_and_b32_e32 v41, 0xffff0000, v38
	v_lshlrev_b32_e32 v38, 16, v39
	v_and_b32_e32 v39, 0xffff0000, v39
	v_and_b32_e32 v37, 0xffff0000, v34
	v_lshlrev_b32_e32 v34, 16, v35
	v_and_b32_e32 v35, 0xffff0000, v35
	v_pk_mul_f32 v[56:57], v[0:1], v[40:41] op_sel_hi:[0,1]
	v_pk_mul_f32 v[38:39], v[0:1], v[38:39] op_sel_hi:[0,1]
	v_pk_fma_f32 v[40:41], v[4:5], v[38:39], v[34:35]
	v_pk_fma_f32 v[38:39], v[2:3], v[56:57], v[36:37]
	global_load_dwordx2 v[34:35], v[60:61], off offset:512 nt
	global_load_dwordx2 v[56:57], v[66:67], off offset:512 nt
	global_load_dwordx2 v[36:37], v[44:45], off offset:512
	global_load_dwordx2 v[58:59], v[42:43], off offset:512
	s_waitcnt vmcnt(3)
	v_lshlrev_b32_e32 v62, 16, v34
	s_waitcnt vmcnt(1)
	v_lshlrev_b32_e32 v64, 16, v36
	v_and_b32_e32 v65, 0xffff0000, v36
	v_lshlrev_b32_e32 v36, 16, v37
	v_and_b32_e32 v37, 0xffff0000, v37
	v_and_b32_e32 v63, 0xffff0000, v34
	v_lshlrev_b32_e32 v34, 16, v35
	v_and_b32_e32 v35, 0xffff0000, v35
	v_pk_mul_f32 v[64:65], v[0:1], v[64:65] op_sel_hi:[0,1]
	v_pk_mul_f32 v[36:37], v[0:1], v[36:37] op_sel_hi:[0,1]
	v_pk_fma_f32 v[36:37], v[8:9], v[36:37], v[34:35]
	v_pk_fma_f32 v[34:35], v[6:7], v[64:65], v[62:63]
	global_load_dwordx2 v[74:75], v[60:61], off offset:1024 nt
	global_load_dwordx2 v[62:63], v[66:67], off offset:1024 nt
	global_load_dwordx2 v[72:73], v[44:45], off offset:1024
	global_load_dwordx2 v[64:65], v[42:43], off offset:1024
	global_load_dwordx2 v[70:71], v[60:61], off offset:1536 nt
	s_nop 0
	global_load_dwordx2 v[66:67], v[66:67], off offset:1536 nt
	s_nop 0
	global_load_dwordx2 v[44:45], v[44:45], off offset:1536
	s_nop 0
	global_load_dwordx2 v[68:69], v[42:43], off offset:1536
	v_lshl_add_u64 v[60:61], v[50:51], 0, s[44:45]
	global_store_dwordx4 v[60:61], v[38:41], off sc1
	s_cbranch_scc0 .LBB0_780
	global_store_dwordx4 v[60:61], v[34:37], off offset:1024 sc1
	s_mov_b64 s[38:39], 0
